# loop back-edge rotation (docs 7.11): counter / address / exit-test SALU hoisted above the loop-back barrier in the P1, P4, P5, P6' K-loops, on top of v071
# baseline (speedup 1.0000x reference)
.LBB0_123:
	ds_read_b128 v[128:131], v190
	ds_read_b128 v[132:135], v190 offset:1024
	ds_read_b128 v[136:139], v190 offset:2048
	ds_read_b128 v[140:143], v190 offset:3072
	ds_read_b128 v[144:147], v191
	ds_read_b128 v[160:163], v191 offset:1024
	ds_read_b128 v[164:167], v191 offset:2048
	s_waitcnt lgkmcnt(0)
	ds_read_b128 v[168:171], v191 offset:3072
	s_add_u32 s4, s0, 0xfff80080
	s_addc_u32 s5, s1, -1
	s_cmp_eq_u32 s78, 28
	s_cselect_b32 s73, s69, s5
	s_cselect_b32 s72, s68, s4
	s_cselect_b32 s5, s71, s67
	s_cselect_b32 s4, s70, s65
	s_add_i32 s94, s33, 0xc000
	v_lshl_add_u64 v[184:185], s[0:1], 0, v[156:157]
	s_mov_b32 m0, s94
	s_add_i32 s95, s33, 0xe000
	ds_read_b128 v[172:175], v192
	ds_read_b128 v[176:179], v192 offset:1024
	ds_read_b128 v[180:183], v192 offset:2048
	ds_read_b128 v[194:197], v192 offset:3072
	ds_read_b128 v[198:201], v192 offset:4096
	ds_read_b128 v[202:205], v192 offset:5120
	ds_read_b128 v[206:209], v192 offset:6144
	ds_read_b128 v[210:213], v192 offset:7168
	global_load_lds_dwordx4 v[184:185], off
	v_lshl_add_u64 v[184:185], s[0:1], 0, v[158:159]
	s_mov_b32 m0, s95
	s_nop 0
	global_load_lds_dwordx4 v[184:185], off
	s_waitcnt vmcnt(8)
	s_waitcnt lgkmcnt(0)
	s_barrier
	s_setprio 1
	s_waitcnt lgkmcnt(0)
	v_mfma_f32_16x16x32_bf16 v[124:127], v[128:131], v[172:175], v[124:127]
	v_mfma_f32_16x16x32_bf16 v[120:123], v[136:139], v[172:175], v[120:123]
	v_mfma_f32_16x16x32_bf16 v[108:111], v[128:131], v[180:183], v[108:111]
	v_mfma_f32_16x16x32_bf16 v[104:107], v[136:139], v[180:183], v[104:107]
	v_mfma_f32_16x16x32_bf16 v[92:95], v[128:131], v[198:201], v[92:95]
	v_mfma_f32_16x16x32_bf16 v[88:91], v[136:139], v[198:201], v[88:91]
	v_mfma_f32_16x16x32_bf16 v[76:79], v[128:131], v[206:209], v[76:79]
	v_mfma_f32_16x16x32_bf16 v[72:75], v[136:139], v[206:209], v[72:75]
	v_mfma_f32_16x16x32_bf16 v[124:127], v[132:135], v[176:179], v[124:127]
	v_mfma_f32_16x16x32_bf16 v[120:123], v[140:143], v[176:179], v[120:123]
	v_mfma_f32_16x16x32_bf16 v[108:111], v[132:135], v[194:197], v[108:111]
	v_mfma_f32_16x16x32_bf16 v[104:107], v[140:143], v[194:197], v[104:107]
	v_mfma_f32_16x16x32_bf16 v[92:95], v[132:135], v[202:205], v[92:95]
	v_mfma_f32_16x16x32_bf16 v[88:91], v[140:143], v[202:205], v[88:91]
	v_mfma_f32_16x16x32_bf16 v[76:79], v[132:135], v[210:213], v[76:79]
	v_mfma_f32_16x16x32_bf16 v[72:75], v[140:143], v[210:213], v[72:75]
	v_mfma_f32_16x16x32_bf16 v[116:119], v[144:147], v[172:175], v[116:119]
	v_mfma_f32_16x16x32_bf16 v[112:115], v[164:167], v[172:175], v[112:115]
	v_mfma_f32_16x16x32_bf16 v[100:103], v[144:147], v[180:183], v[100:103]
	v_mfma_f32_16x16x32_bf16 v[96:99], v[164:167], v[180:183], v[96:99]
	v_mfma_f32_16x16x32_bf16 v[84:87], v[144:147], v[198:201], v[84:87]
	v_mfma_f32_16x16x32_bf16 v[80:83], v[164:167], v[198:201], v[80:83]
	v_mfma_f32_16x16x32_bf16 v[68:71], v[144:147], v[206:209], v[68:71]
	v_mfma_f32_16x16x32_bf16 v[64:67], v[164:167], v[206:209], v[64:67]
	v_mfma_f32_16x16x32_bf16 v[116:119], v[160:163], v[176:179], v[116:119]
	v_mfma_f32_16x16x32_bf16 v[112:115], v[168:171], v[176:179], v[112:115]
	v_mfma_f32_16x16x32_bf16 v[100:103], v[160:163], v[194:197], v[100:103]
	v_mfma_f32_16x16x32_bf16 v[96:99], v[168:171], v[194:197], v[96:99]
	v_mfma_f32_16x16x32_bf16 v[84:87], v[160:163], v[202:205], v[84:87]
	v_mfma_f32_16x16x32_bf16 v[80:83], v[168:171], v[202:205], v[80:83]
	v_mfma_f32_16x16x32_bf16 v[68:71], v[160:163], v[210:213], v[68:71]
	v_mfma_f32_16x16x32_bf16 v[64:67], v[168:171], v[210:213], v[64:67]
	s_setprio 0
	s_barrier
	s_add_i32 s96, s31, s40
	s_add_i32 s97, s96, 0x2000
	v_lshl_add_u64 v[184:185], s[4:5], 0, v[150:151]
	s_mov_b32 m0, s96
	s_add_u32 s26, s4, 0x80000
	ds_read_b128 v[172:175], v192 offset:16384
	ds_read_b128 v[176:179], v192 offset:17408
	ds_read_b128 v[180:183], v192 offset:18432
	ds_read_b128 v[194:197], v192 offset:19456
	ds_read_b128 v[198:201], v192 offset:20480
	ds_read_b128 v[202:205], v192 offset:21504
	ds_read_b128 v[206:209], v192 offset:22528
	ds_read_b128 v[210:213], v192 offset:23552
	global_load_lds_dwordx4 v[184:185], off
	v_lshl_add_u64 v[214:215], s[4:5], 0, v[154:155]
	s_mov_b32 m0, s97
	s_addc_u32 s27, s5, 0
	s_add_i32 s91, s30, s40
	global_load_lds_dwordx4 v[214:215], off
	v_lshl_add_u64 v[216:217], s[26:27], 0, v[150:151]
	s_mov_b32 m0, s91
	v_lshl_add_u64 v[218:219], s[72:73], 0, v[152:153]
	global_load_lds_dwordx4 v[216:217], off
	v_lshl_add_u64 v[216:217], s[26:27], 0, v[154:155]
	s_add_i32 s26, s91, 0x2000
	s_mov_b32 m0, s26
	s_nop 0
	global_load_lds_dwordx4 v[216:217], off
	v_lshl_add_u64 v[216:217], s[72:73], 0, v[148:149]
	s_mov_b32 m0, s33
	s_nop 0
	global_load_lds_dwordx4 v[216:217], off
	s_mov_b32 m0, s88
	s_nop 0
	global_load_lds_dwordx4 v[218:219], off
	s_waitcnt vmcnt(8)
	s_waitcnt lgkmcnt(0)
	s_barrier
	s_setprio 1
	s_waitcnt lgkmcnt(0)
	v_mfma_f32_16x16x32_bf16 v[60:63], v[128:131], v[172:175], v[60:63]
	v_mfma_f32_16x16x32_bf16 v[56:59], v[136:139], v[172:175], v[56:59]
	v_mfma_f32_16x16x32_bf16 v[44:47], v[128:131], v[180:183], v[44:47]
	v_mfma_f32_16x16x32_bf16 v[40:43], v[136:139], v[180:183], v[40:43]
	v_mfma_f32_16x16x32_bf16 v[28:31], v[128:131], v[198:201], v[28:31]
	v_mfma_f32_16x16x32_bf16 v[24:27], v[136:139], v[198:201], v[24:27]
	v_mfma_f32_16x16x32_bf16 v[12:15], v[128:131], v[206:209], v[12:15]
	v_mfma_f32_16x16x32_bf16 v[8:11], v[136:139], v[206:209], v[8:11]
	v_mfma_f32_16x16x32_bf16 v[60:63], v[132:135], v[176:179], v[60:63]
	v_mfma_f32_16x16x32_bf16 v[56:59], v[140:143], v[176:179], v[56:59]
	v_mfma_f32_16x16x32_bf16 v[44:47], v[132:135], v[194:197], v[44:47]
	v_mfma_f32_16x16x32_bf16 v[40:43], v[140:143], v[194:197], v[40:43]
	v_mfma_f32_16x16x32_bf16 v[28:31], v[132:135], v[202:205], v[28:31]
	v_mfma_f32_16x16x32_bf16 v[24:27], v[140:143], v[202:205], v[24:27]
	v_mfma_f32_16x16x32_bf16 v[12:15], v[132:135], v[210:213], v[12:15]
	v_mfma_f32_16x16x32_bf16 v[8:11], v[140:143], v[210:213], v[8:11]
	v_mfma_f32_16x16x32_bf16 v[52:55], v[144:147], v[172:175], v[52:55]
	v_mfma_f32_16x16x32_bf16 v[48:51], v[164:167], v[172:175], v[48:51]
	v_mfma_f32_16x16x32_bf16 v[36:39], v[144:147], v[180:183], v[36:39]
	v_mfma_f32_16x16x32_bf16 v[32:35], v[164:167], v[180:183], v[32:35]
	v_mfma_f32_16x16x32_bf16 v[20:23], v[144:147], v[198:201], v[20:23]
	v_mfma_f32_16x16x32_bf16 v[16:19], v[164:167], v[198:201], v[16:19]
	v_mfma_f32_16x16x32_bf16 v[4:7], v[144:147], v[206:209], v[4:7]
	v_mfma_f32_16x16x32_bf16 v[0:3], v[164:167], v[206:209], v[0:3]
	v_mfma_f32_16x16x32_bf16 v[52:55], v[160:163], v[176:179], v[52:55]
	v_mfma_f32_16x16x32_bf16 v[48:51], v[168:171], v[176:179], v[48:51]
	v_mfma_f32_16x16x32_bf16 v[36:39], v[160:163], v[194:197], v[36:39]
	v_mfma_f32_16x16x32_bf16 v[32:35], v[168:171], v[194:197], v[32:35]
	v_mfma_f32_16x16x32_bf16 v[20:23], v[160:163], v[202:205], v[20:23]
	v_mfma_f32_16x16x32_bf16 v[16:19], v[168:171], v[202:205], v[16:19]
	v_mfma_f32_16x16x32_bf16 v[4:7], v[160:163], v[210:213], v[4:7]
	v_mfma_f32_16x16x32_bf16 v[0:3], v[168:171], v[210:213], v[0:3]
	s_setprio 0
	s_barrier
	s_add_i32 s29, 0, 0x18000
	s_add_i32 s41, 0, 0x1c000
	v_add_u32_e32 v140, s29, v189
	v_add_u32_e32 v168, s41, v189
	ds_read_b128 v[128:131], v140
	ds_read_b128 v[132:135], v140 offset:1024
	ds_read_b128 v[136:139], v140 offset:2048
	ds_read_b128 v[140:143], v140 offset:3072
	ds_read_b128 v[144:147], v168
	ds_read_b128 v[160:163], v168 offset:1024
	ds_read_b128 v[164:167], v168 offset:2048
	ds_read_b128 v[168:171], v168 offset:3072
	s_add_u32 s34, s72, 0x80000
	s_addc_u32 s35, s73, 0
	s_mov_b32 m0, s89
	v_lshl_add_u64 v[220:221], s[34:35], 0, v[148:149]
	ds_read_b128 v[172:175], v192 offset:32768
	ds_read_b128 v[176:179], v192 offset:33792
	ds_read_b128 v[180:183], v192 offset:34816
	ds_read_b128 v[194:197], v192 offset:35840
	ds_read_b128 v[198:201], v192 offset:36864
	ds_read_b128 v[202:205], v192 offset:37888
	ds_read_b128 v[206:209], v192 offset:38912
	ds_read_b128 v[210:213], v192 offset:39936
	global_load_lds_dwordx4 v[220:221], off
	v_lshl_add_u64 v[220:221], s[34:35], 0, v[152:153]
	s_mov_b32 m0, s90
	s_nop 0
	global_load_lds_dwordx4 v[220:221], off
	s_waitcnt vmcnt(8)
	s_waitcnt lgkmcnt(0)
	s_barrier
	s_setprio 1
	s_waitcnt lgkmcnt(0)
	v_mfma_f32_16x16x32_bf16 v[124:127], v[128:131], v[172:175], v[124:127]
	v_mfma_f32_16x16x32_bf16 v[120:123], v[136:139], v[172:175], v[120:123]
	v_mfma_f32_16x16x32_bf16 v[108:111], v[128:131], v[180:183], v[108:111]
	v_mfma_f32_16x16x32_bf16 v[104:107], v[136:139], v[180:183], v[104:107]
	v_mfma_f32_16x16x32_bf16 v[92:95], v[128:131], v[198:201], v[92:95]
	v_mfma_f32_16x16x32_bf16 v[88:91], v[136:139], v[198:201], v[88:91]
	v_mfma_f32_16x16x32_bf16 v[76:79], v[128:131], v[206:209], v[76:79]
	v_mfma_f32_16x16x32_bf16 v[72:75], v[136:139], v[206:209], v[72:75]
	v_mfma_f32_16x16x32_bf16 v[124:127], v[132:135], v[176:179], v[124:127]
	v_mfma_f32_16x16x32_bf16 v[120:123], v[140:143], v[176:179], v[120:123]
	v_mfma_f32_16x16x32_bf16 v[108:111], v[132:135], v[194:197], v[108:111]
	v_mfma_f32_16x16x32_bf16 v[104:107], v[140:143], v[194:197], v[104:107]
	v_mfma_f32_16x16x32_bf16 v[92:95], v[132:135], v[202:205], v[92:95]
	v_mfma_f32_16x16x32_bf16 v[88:91], v[140:143], v[202:205], v[88:91]
	v_mfma_f32_16x16x32_bf16 v[76:79], v[132:135], v[210:213], v[76:79]
	v_mfma_f32_16x16x32_bf16 v[72:75], v[140:143], v[210:213], v[72:75]
	v_mfma_f32_16x16x32_bf16 v[116:119], v[144:147], v[172:175], v[116:119]
	v_mfma_f32_16x16x32_bf16 v[112:115], v[164:167], v[172:175], v[112:115]
	v_mfma_f32_16x16x32_bf16 v[100:103], v[144:147], v[180:183], v[100:103]
	v_mfma_f32_16x16x32_bf16 v[96:99], v[164:167], v[180:183], v[96:99]
	v_mfma_f32_16x16x32_bf16 v[84:87], v[144:147], v[198:201], v[84:87]
	v_mfma_f32_16x16x32_bf16 v[80:83], v[164:167], v[198:201], v[80:83]
	v_mfma_f32_16x16x32_bf16 v[68:71], v[144:147], v[206:209], v[68:71]
	v_mfma_f32_16x16x32_bf16 v[64:67], v[164:167], v[206:209], v[64:67]
	v_mfma_f32_16x16x32_bf16 v[116:119], v[160:163], v[176:179], v[116:119]
	v_mfma_f32_16x16x32_bf16 v[112:115], v[168:171], v[176:179], v[112:115]
	v_mfma_f32_16x16x32_bf16 v[100:103], v[160:163], v[194:197], v[100:103]
	v_mfma_f32_16x16x32_bf16 v[96:99], v[168:171], v[194:197], v[96:99]
	v_mfma_f32_16x16x32_bf16 v[84:87], v[160:163], v[202:205], v[84:87]
	v_mfma_f32_16x16x32_bf16 v[80:83], v[168:171], v[202:205], v[80:83]
	v_mfma_f32_16x16x32_bf16 v[68:71], v[160:163], v[210:213], v[68:71]
	v_mfma_f32_16x16x32_bf16 v[64:67], v[168:171], v[210:213], v[64:67]
	s_setprio 0
	s_barrier
	s_add_i32 s27, s29, s40
	s_add_i32 s34, s27, 0x2000
	v_lshl_add_u64 v[184:185], v[184:185], 0, s[48:49]
	s_mov_b32 m0, s27
	s_add_u32 s4, s4, 0x80080
	ds_read_b128 v[172:175], v192 offset:49152
	ds_read_b128 v[176:179], v192 offset:50176
	ds_read_b128 v[180:183], v192 offset:51200
	ds_read_b128 v[194:197], v192 offset:52224
	ds_read_b128 v[198:201], v192 offset:53248
	ds_read_b128 v[202:205], v192 offset:54272
	ds_read_b128 v[206:209], v192 offset:55296
	ds_read_b128 v[210:213], v192 offset:56320
	global_load_lds_dwordx4 v[184:185], off
	v_lshl_add_u64 v[184:185], v[214:215], 0, s[48:49]
	s_mov_b32 m0, s34
	s_addc_u32 s5, s5, 0
	s_add_i32 s35, s41, s40
	global_load_lds_dwordx4 v[184:185], off
	v_lshl_add_u64 v[184:185], s[4:5], 0, v[150:151]
	s_mov_b32 m0, s35
	s_add_i32 s28, s35, 0x2000
	global_load_lds_dwordx4 v[184:185], off
	v_lshl_add_u64 v[184:185], s[4:5], 0, v[154:155]
	s_mov_b32 m0, s28
	s_nop 0
	global_load_lds_dwordx4 v[184:185], off
	v_lshl_add_u64 v[184:185], v[216:217], 0, s[48:49]
	s_mov_b32 m0, s92
	s_nop 0
	global_load_lds_dwordx4 v[184:185], off
	v_lshl_add_u64 v[184:185], v[218:219], 0, s[48:49]
	s_mov_b32 m0, s93
	s_nop 0
	global_load_lds_dwordx4 v[184:185], off
	s_waitcnt vmcnt(8)
	s_waitcnt lgkmcnt(0)
	s_barrier
	s_setprio 1
	s_waitcnt lgkmcnt(0)
	v_mfma_f32_16x16x32_bf16 v[60:63], v[128:131], v[172:175], v[60:63]
	v_mfma_f32_16x16x32_bf16 v[56:59], v[136:139], v[172:175], v[56:59]
	v_mfma_f32_16x16x32_bf16 v[44:47], v[128:131], v[180:183], v[44:47]
	v_mfma_f32_16x16x32_bf16 v[40:43], v[136:139], v[180:183], v[40:43]
	v_mfma_f32_16x16x32_bf16 v[28:31], v[128:131], v[198:201], v[28:31]
	v_mfma_f32_16x16x32_bf16 v[24:27], v[136:139], v[198:201], v[24:27]
	v_mfma_f32_16x16x32_bf16 v[12:15], v[128:131], v[206:209], v[12:15]
	v_mfma_f32_16x16x32_bf16 v[8:11], v[136:139], v[206:209], v[8:11]
	v_mfma_f32_16x16x32_bf16 v[60:63], v[132:135], v[176:179], v[60:63]
	v_mfma_f32_16x16x32_bf16 v[56:59], v[140:143], v[176:179], v[56:59]
	v_mfma_f32_16x16x32_bf16 v[44:47], v[132:135], v[194:197], v[44:47]
	v_mfma_f32_16x16x32_bf16 v[40:43], v[140:143], v[194:197], v[40:43]
	v_mfma_f32_16x16x32_bf16 v[28:31], v[132:135], v[202:205], v[28:31]
	v_mfma_f32_16x16x32_bf16 v[24:27], v[140:143], v[202:205], v[24:27]
	v_mfma_f32_16x16x32_bf16 v[12:15], v[132:135], v[210:213], v[12:15]
	v_mfma_f32_16x16x32_bf16 v[8:11], v[140:143], v[210:213], v[8:11]
	v_mfma_f32_16x16x32_bf16 v[52:55], v[144:147], v[172:175], v[52:55]
	v_mfma_f32_16x16x32_bf16 v[48:51], v[164:167], v[172:175], v[48:51]
	v_mfma_f32_16x16x32_bf16 v[36:39], v[144:147], v[180:183], v[36:39]
	v_mfma_f32_16x16x32_bf16 v[32:35], v[164:167], v[180:183], v[32:35]
	v_mfma_f32_16x16x32_bf16 v[20:23], v[144:147], v[198:201], v[20:23]
	v_mfma_f32_16x16x32_bf16 v[16:19], v[164:167], v[198:201], v[16:19]
	v_mfma_f32_16x16x32_bf16 v[4:7], v[144:147], v[206:209], v[4:7]
	v_mfma_f32_16x16x32_bf16 v[0:3], v[164:167], v[206:209], v[0:3]
	v_mfma_f32_16x16x32_bf16 v[52:55], v[160:163], v[176:179], v[52:55]
	v_mfma_f32_16x16x32_bf16 v[48:51], v[168:171], v[176:179], v[48:51]
	v_mfma_f32_16x16x32_bf16 v[36:39], v[160:163], v[194:197], v[36:39]
	v_mfma_f32_16x16x32_bf16 v[32:35], v[168:171], v[194:197], v[32:35]
	v_mfma_f32_16x16x32_bf16 v[20:23], v[160:163], v[202:205], v[20:23]
	v_mfma_f32_16x16x32_bf16 v[16:19], v[168:171], v[202:205], v[16:19]
	v_mfma_f32_16x16x32_bf16 v[4:7], v[160:163], v[210:213], v[4:7]
	v_mfma_f32_16x16x32_bf16 v[0:3], v[168:171], v[210:213], v[0:3]
	s_setprio 0
	s_add_i32 s78, s78, 2
	s_add_u32 s0, s0, 0x100
	s_addc_u32 s1, s1, 0
	s_add_u32 s65, s65, 0x100
	s_addc_u32 s67, s67, 0
	s_cmp_gt_u32 s78, 29
	s_barrier
	s_cbranch_scc0 .LBB0_123
	s_and_b64 vcc, exec, s[42:43]
	s_cbranch_vccz .LBB0_126
	s_barrier

.LBB0_413:
	ds_read_b128 v[144:147], v155
	ds_read_b128 v[148:151], v155 offset:1024
	ds_read_b128 v[158:161], v155 offset:2048
	ds_read_b128 v[162:165], v155 offset:3072
	ds_read_b128 v[166:169], v156
	ds_read_b128 v[170:173], v156 offset:1024
	ds_read_b128 v[174:177], v156 offset:2048
	ds_read_b128 v[178:181], v156 offset:3072
	s_add_u32 s21, s50, 0xfff80080
	s_addc_u32 s52, s51, -1
	s_cmp_eq_u32 s45, 28
	s_cselect_b32 s55, s9, s52
	s_cselect_b32 s54, s8, s21
	s_cselect_b32 s53, s43, s25
	s_cselect_b32 s52, s42, s23
	s_add_u32 s58, s52, 0x80000
	s_addc_u32 s59, s53, 0
	s_mov_b32 m0, s94
	ds_read_b128 v[182:185], v157
	ds_read_b128 v[188:191], v157 offset:1024
	ds_read_b128 v[192:195], v157 offset:2048
	ds_read_b128 v[196:199], v157 offset:3072
	ds_read_b128 v[200:203], v157 offset:4096
	ds_read_b128 v[204:207], v157 offset:5120
	ds_read_b128 v[208:211], v157 offset:6144
	ds_read_b128 v[212:215], v157 offset:7168
	global_load_lds_dwordx4 v136, s[50:51]
	s_mov_b32 m0, s95
	s_nop 0
	global_load_lds_dwordx4 v138, s[50:51]
	s_waitcnt vmcnt(8)
	s_waitcnt lgkmcnt(0)
	s_barrier
	s_setprio 1
	s_waitcnt lgkmcnt(0)
	v_mfma_f32_16x16x32_bf16 v[124:127], v[144:147], v[182:185], v[124:127]
	v_mfma_f32_16x16x32_bf16 v[120:123], v[158:161], v[182:185], v[120:123]
	v_mfma_f32_16x16x32_bf16 v[108:111], v[144:147], v[192:195], v[108:111]
	v_mfma_f32_16x16x32_bf16 v[104:107], v[158:161], v[192:195], v[104:107]
	v_mfma_f32_16x16x32_bf16 v[92:95], v[144:147], v[200:203], v[92:95]
	v_mfma_f32_16x16x32_bf16 v[88:91], v[158:161], v[200:203], v[88:91]
	v_mfma_f32_16x16x32_bf16 v[76:79], v[144:147], v[208:211], v[76:79]
	v_mfma_f32_16x16x32_bf16 v[72:75], v[158:161], v[208:211], v[72:75]
	v_mfma_f32_16x16x32_bf16 v[124:127], v[148:151], v[188:191], v[124:127]
	v_mfma_f32_16x16x32_bf16 v[120:123], v[162:165], v[188:191], v[120:123]
	v_mfma_f32_16x16x32_bf16 v[108:111], v[148:151], v[196:199], v[108:111]
	v_mfma_f32_16x16x32_bf16 v[104:107], v[162:165], v[196:199], v[104:107]
	v_mfma_f32_16x16x32_bf16 v[92:95], v[148:151], v[204:207], v[92:95]
	v_mfma_f32_16x16x32_bf16 v[88:91], v[162:165], v[204:207], v[88:91]
	v_mfma_f32_16x16x32_bf16 v[76:79], v[148:151], v[212:215], v[76:79]
	v_mfma_f32_16x16x32_bf16 v[72:75], v[162:165], v[212:215], v[72:75]
	v_mfma_f32_16x16x32_bf16 v[116:119], v[166:169], v[182:185], v[116:119]
	v_mfma_f32_16x16x32_bf16 v[112:115], v[174:177], v[182:185], v[112:115]
	v_mfma_f32_16x16x32_bf16 v[100:103], v[166:169], v[192:195], v[100:103]
	v_mfma_f32_16x16x32_bf16 v[96:99], v[174:177], v[192:195], v[96:99]
	v_mfma_f32_16x16x32_bf16 v[84:87], v[166:169], v[200:203], v[84:87]
	v_mfma_f32_16x16x32_bf16 v[80:83], v[174:177], v[200:203], v[80:83]
	v_mfma_f32_16x16x32_bf16 v[68:71], v[166:169], v[208:211], v[68:71]
	v_mfma_f32_16x16x32_bf16 v[64:67], v[174:177], v[208:211], v[64:67]
	v_mfma_f32_16x16x32_bf16 v[116:119], v[170:173], v[188:191], v[116:119]
	v_mfma_f32_16x16x32_bf16 v[112:115], v[178:181], v[188:191], v[112:115]
	v_mfma_f32_16x16x32_bf16 v[100:103], v[170:173], v[196:199], v[100:103]
	v_mfma_f32_16x16x32_bf16 v[96:99], v[178:181], v[196:199], v[96:99]
	v_mfma_f32_16x16x32_bf16 v[84:87], v[170:173], v[204:207], v[84:87]
	v_mfma_f32_16x16x32_bf16 v[80:83], v[178:181], v[204:207], v[80:83]
	v_mfma_f32_16x16x32_bf16 v[68:71], v[170:173], v[212:215], v[68:71]
	v_mfma_f32_16x16x32_bf16 v[64:67], v[178:181], v[212:215], v[64:67]
	s_setprio 0
	s_barrier
	s_mov_b32 m0, s96
	s_add_u32 s98, s54, 0x80000
	s_addc_u32 s99, s55, 0
	ds_read_b128 v[182:185], v157 offset:16384
	ds_read_b128 v[188:191], v157 offset:17408
	ds_read_b128 v[192:195], v157 offset:18432
	ds_read_b128 v[196:199], v157 offset:19456
	ds_read_b128 v[200:203], v157 offset:20480
	ds_read_b128 v[204:207], v157 offset:21504
	ds_read_b128 v[208:211], v157 offset:22528
	ds_read_b128 v[212:215], v157 offset:23552
	global_load_lds_dwordx4 v130, s[52:53]
	s_mov_b32 m0, s97
	s_nop 0
	global_load_lds_dwordx4 v134, s[52:53]
	s_mov_b32 m0, s91
	s_nop 0
	global_load_lds_dwordx4 v130, s[58:59]
	s_mov_b32 m0, s26
	s_nop 0
	global_load_lds_dwordx4 v134, s[58:59]
	s_mov_b32 m0, s33
	s_nop 0
	global_load_lds_dwordx4 v128, s[54:55]
	s_mov_b32 m0, s88
	s_nop 0
	global_load_lds_dwordx4 v132, s[54:55]
	s_waitcnt vmcnt(8)
	s_waitcnt lgkmcnt(0)
	s_barrier
	s_setprio 1
	s_waitcnt lgkmcnt(0)
	v_mfma_f32_16x16x32_bf16 v[60:63], v[144:147], v[182:185], v[60:63]
	v_mfma_f32_16x16x32_bf16 v[56:59], v[158:161], v[182:185], v[56:59]
	v_mfma_f32_16x16x32_bf16 v[44:47], v[144:147], v[192:195], v[44:47]
	v_mfma_f32_16x16x32_bf16 v[40:43], v[158:161], v[192:195], v[40:43]
	v_mfma_f32_16x16x32_bf16 v[28:31], v[144:147], v[200:203], v[28:31]
	v_mfma_f32_16x16x32_bf16 v[24:27], v[158:161], v[200:203], v[24:27]
	v_mfma_f32_16x16x32_bf16 v[12:15], v[144:147], v[208:211], v[12:15]
	v_mfma_f32_16x16x32_bf16 v[8:11], v[158:161], v[208:211], v[8:11]
	v_mfma_f32_16x16x32_bf16 v[60:63], v[148:151], v[188:191], v[60:63]
	v_mfma_f32_16x16x32_bf16 v[56:59], v[162:165], v[188:191], v[56:59]
	v_mfma_f32_16x16x32_bf16 v[44:47], v[148:151], v[196:199], v[44:47]
	v_mfma_f32_16x16x32_bf16 v[40:43], v[162:165], v[196:199], v[40:43]
	v_mfma_f32_16x16x32_bf16 v[28:31], v[148:151], v[204:207], v[28:31]
	v_mfma_f32_16x16x32_bf16 v[24:27], v[162:165], v[204:207], v[24:27]
	v_mfma_f32_16x16x32_bf16 v[12:15], v[148:151], v[212:215], v[12:15]
	v_mfma_f32_16x16x32_bf16 v[8:11], v[162:165], v[212:215], v[8:11]
	v_mfma_f32_16x16x32_bf16 v[52:55], v[166:169], v[182:185], v[52:55]
	v_mfma_f32_16x16x32_bf16 v[48:51], v[174:177], v[182:185], v[48:51]
	v_mfma_f32_16x16x32_bf16 v[36:39], v[166:169], v[192:195], v[36:39]
	v_mfma_f32_16x16x32_bf16 v[32:35], v[174:177], v[192:195], v[32:35]
	v_mfma_f32_16x16x32_bf16 v[20:23], v[166:169], v[200:203], v[20:23]
	v_mfma_f32_16x16x32_bf16 v[16:19], v[174:177], v[200:203], v[16:19]
	v_mfma_f32_16x16x32_bf16 v[4:7], v[166:169], v[208:211], v[4:7]
	v_mfma_f32_16x16x32_bf16 v[0:3], v[174:177], v[208:211], v[0:3]
	v_mfma_f32_16x16x32_bf16 v[52:55], v[170:173], v[188:191], v[52:55]
	v_mfma_f32_16x16x32_bf16 v[48:51], v[178:181], v[188:191], v[48:51]
	v_mfma_f32_16x16x32_bf16 v[36:39], v[170:173], v[196:199], v[36:39]
	v_mfma_f32_16x16x32_bf16 v[32:35], v[178:181], v[196:199], v[32:35]
	v_mfma_f32_16x16x32_bf16 v[20:23], v[170:173], v[204:207], v[20:23]
	v_mfma_f32_16x16x32_bf16 v[16:19], v[178:181], v[204:207], v[16:19]
	v_mfma_f32_16x16x32_bf16 v[4:7], v[170:173], v[212:215], v[4:7]
	v_mfma_f32_16x16x32_bf16 v[0:3], v[178:181], v[212:215], v[0:3]
	s_setprio 0
	s_barrier
	v_add_u32_e32 v162, s29, v153
	v_add_u32_e32 v178, s41, v153
	ds_read_b128 v[144:147], v162
	ds_read_b128 v[148:151], v162 offset:1024
	ds_read_b128 v[158:161], v162 offset:2048
	ds_read_b128 v[162:165], v162 offset:3072
	ds_read_b128 v[166:169], v178
	ds_read_b128 v[170:173], v178 offset:1024
	ds_read_b128 v[174:177], v178 offset:2048
	ds_read_b128 v[178:181], v178 offset:3072
	s_mov_b32 m0, s89
	s_add_u32 s100, s52, 0x80
	s_addc_u32 s101, s53, 0
	ds_read_b128 v[182:185], v157 offset:32768
	ds_read_b128 v[188:191], v157 offset:33792
	ds_read_b128 v[192:195], v157 offset:34816
	ds_read_b128 v[196:199], v157 offset:35840
	ds_read_b128 v[200:203], v157 offset:36864
	ds_read_b128 v[204:207], v157 offset:37888
	ds_read_b128 v[208:211], v157 offset:38912
	ds_read_b128 v[212:215], v157 offset:39936
	global_load_lds_dwordx4 v128, s[98:99]
	s_mov_b32 m0, s90
	s_add_u32 s58, s52, 0x80080
	s_addc_u32 s59, s53, 0
	global_load_lds_dwordx4 v132, s[98:99]
	s_add_u32 s98, s54, 0x80
	s_addc_u32 s99, s55, 0
	s_waitcnt vmcnt(8)
	s_waitcnt lgkmcnt(0)
	s_barrier
	s_setprio 1
	s_waitcnt lgkmcnt(0)
	v_mfma_f32_16x16x32_bf16 v[124:127], v[144:147], v[182:185], v[124:127]
	v_mfma_f32_16x16x32_bf16 v[120:123], v[158:161], v[182:185], v[120:123]
	v_mfma_f32_16x16x32_bf16 v[108:111], v[144:147], v[192:195], v[108:111]
	v_mfma_f32_16x16x32_bf16 v[104:107], v[158:161], v[192:195], v[104:107]
	v_mfma_f32_16x16x32_bf16 v[92:95], v[144:147], v[200:203], v[92:95]
	v_mfma_f32_16x16x32_bf16 v[88:91], v[158:161], v[200:203], v[88:91]
	v_mfma_f32_16x16x32_bf16 v[76:79], v[144:147], v[208:211], v[76:79]
	v_mfma_f32_16x16x32_bf16 v[72:75], v[158:161], v[208:211], v[72:75]
	v_mfma_f32_16x16x32_bf16 v[124:127], v[148:151], v[188:191], v[124:127]
	v_mfma_f32_16x16x32_bf16 v[120:123], v[162:165], v[188:191], v[120:123]
	v_mfma_f32_16x16x32_bf16 v[108:111], v[148:151], v[196:199], v[108:111]
	v_mfma_f32_16x16x32_bf16 v[104:107], v[162:165], v[196:199], v[104:107]
	v_mfma_f32_16x16x32_bf16 v[92:95], v[148:151], v[204:207], v[92:95]
	v_mfma_f32_16x16x32_bf16 v[88:91], v[162:165], v[204:207], v[88:91]
	v_mfma_f32_16x16x32_bf16 v[76:79], v[148:151], v[212:215], v[76:79]
	v_mfma_f32_16x16x32_bf16 v[72:75], v[162:165], v[212:215], v[72:75]
	v_mfma_f32_16x16x32_bf16 v[116:119], v[166:169], v[182:185], v[116:119]
	v_mfma_f32_16x16x32_bf16 v[112:115], v[174:177], v[182:185], v[112:115]
	v_mfma_f32_16x16x32_bf16 v[100:103], v[166:169], v[192:195], v[100:103]
	v_mfma_f32_16x16x32_bf16 v[96:99], v[174:177], v[192:195], v[96:99]
	v_mfma_f32_16x16x32_bf16 v[84:87], v[166:169], v[200:203], v[84:87]
	v_mfma_f32_16x16x32_bf16 v[80:83], v[174:177], v[200:203], v[80:83]
	v_mfma_f32_16x16x32_bf16 v[68:71], v[166:169], v[208:211], v[68:71]
	v_mfma_f32_16x16x32_bf16 v[64:67], v[174:177], v[208:211], v[64:67]
	v_mfma_f32_16x16x32_bf16 v[116:119], v[170:173], v[188:191], v[116:119]
	v_mfma_f32_16x16x32_bf16 v[112:115], v[178:181], v[188:191], v[112:115]
	v_mfma_f32_16x16x32_bf16 v[100:103], v[170:173], v[196:199], v[100:103]
	v_mfma_f32_16x16x32_bf16 v[96:99], v[178:181], v[196:199], v[96:99]
	v_mfma_f32_16x16x32_bf16 v[84:87], v[170:173], v[204:207], v[84:87]
	v_mfma_f32_16x16x32_bf16 v[80:83], v[178:181], v[204:207], v[80:83]
	v_mfma_f32_16x16x32_bf16 v[68:71], v[170:173], v[212:215], v[68:71]
	v_mfma_f32_16x16x32_bf16 v[64:67], v[178:181], v[212:215], v[64:67]
	s_setprio 0
	s_barrier
	s_mov_b32 m0, s27
	s_nop 0
	ds_read_b128 v[182:185], v157 offset:49152
	ds_read_b128 v[188:191], v157 offset:50176
	ds_read_b128 v[192:195], v157 offset:51200
	ds_read_b128 v[196:199], v157 offset:52224
	ds_read_b128 v[200:203], v157 offset:53248
	ds_read_b128 v[204:207], v157 offset:54272
	ds_read_b128 v[208:211], v157 offset:55296
	ds_read_b128 v[212:215], v157 offset:56320
	global_load_lds_dwordx4 v130, s[100:101]
	s_mov_b32 m0, s34
	s_nop 0
	global_load_lds_dwordx4 v134, s[100:101]
	s_mov_b32 m0, s35
	s_nop 0
	global_load_lds_dwordx4 v130, s[58:59]
	s_mov_b32 m0, s28
	s_nop 0
	global_load_lds_dwordx4 v134, s[58:59]
	s_mov_b32 m0, s92
	s_nop 0
	global_load_lds_dwordx4 v128, s[98:99]
	s_mov_b32 m0, s93
	s_nop 0
	global_load_lds_dwordx4 v132, s[98:99]
	s_waitcnt vmcnt(8)
	s_waitcnt lgkmcnt(0)
	s_barrier
	s_setprio 1
	s_waitcnt lgkmcnt(0)
	v_mfma_f32_16x16x32_bf16 v[60:63], v[144:147], v[182:185], v[60:63]
	v_mfma_f32_16x16x32_bf16 v[56:59], v[158:161], v[182:185], v[56:59]
	v_mfma_f32_16x16x32_bf16 v[44:47], v[144:147], v[192:195], v[44:47]
	v_mfma_f32_16x16x32_bf16 v[40:43], v[158:161], v[192:195], v[40:43]
	v_mfma_f32_16x16x32_bf16 v[28:31], v[144:147], v[200:203], v[28:31]
	v_mfma_f32_16x16x32_bf16 v[24:27], v[158:161], v[200:203], v[24:27]
	v_mfma_f32_16x16x32_bf16 v[12:15], v[144:147], v[208:211], v[12:15]
	v_mfma_f32_16x16x32_bf16 v[8:11], v[158:161], v[208:211], v[8:11]
	v_mfma_f32_16x16x32_bf16 v[60:63], v[148:151], v[188:191], v[60:63]
	v_mfma_f32_16x16x32_bf16 v[56:59], v[162:165], v[188:191], v[56:59]
	v_mfma_f32_16x16x32_bf16 v[44:47], v[148:151], v[196:199], v[44:47]
	v_mfma_f32_16x16x32_bf16 v[40:43], v[162:165], v[196:199], v[40:43]
	v_mfma_f32_16x16x32_bf16 v[28:31], v[148:151], v[204:207], v[28:31]
	v_mfma_f32_16x16x32_bf16 v[24:27], v[162:165], v[204:207], v[24:27]
	v_mfma_f32_16x16x32_bf16 v[12:15], v[148:151], v[212:215], v[12:15]
	v_mfma_f32_16x16x32_bf16 v[8:11], v[162:165], v[212:215], v[8:11]
	v_mfma_f32_16x16x32_bf16 v[52:55], v[166:169], v[182:185], v[52:55]
	v_mfma_f32_16x16x32_bf16 v[48:51], v[174:177], v[182:185], v[48:51]
	v_mfma_f32_16x16x32_bf16 v[36:39], v[166:169], v[192:195], v[36:39]
	v_mfma_f32_16x16x32_bf16 v[32:35], v[174:177], v[192:195], v[32:35]
	v_mfma_f32_16x16x32_bf16 v[20:23], v[166:169], v[200:203], v[20:23]
	v_mfma_f32_16x16x32_bf16 v[16:19], v[174:177], v[200:203], v[16:19]
	v_mfma_f32_16x16x32_bf16 v[4:7], v[166:169], v[208:211], v[4:7]
	v_mfma_f32_16x16x32_bf16 v[0:3], v[174:177], v[208:211], v[0:3]
	v_mfma_f32_16x16x32_bf16 v[52:55], v[170:173], v[188:191], v[52:55]
	v_mfma_f32_16x16x32_bf16 v[48:51], v[178:181], v[188:191], v[48:51]
	v_mfma_f32_16x16x32_bf16 v[36:39], v[170:173], v[196:199], v[36:39]
	v_mfma_f32_16x16x32_bf16 v[32:35], v[178:181], v[196:199], v[32:35]
	v_mfma_f32_16x16x32_bf16 v[20:23], v[170:173], v[204:207], v[20:23]
	v_mfma_f32_16x16x32_bf16 v[16:19], v[178:181], v[204:207], v[16:19]
	v_mfma_f32_16x16x32_bf16 v[4:7], v[170:173], v[212:215], v[4:7]
	v_mfma_f32_16x16x32_bf16 v[0:3], v[178:181], v[212:215], v[0:3]
	s_setprio 0
	s_add_i32 s45, s45, 2
	s_add_u32 s50, s50, 0x100
	s_addc_u32 s51, s51, 0
	s_add_u32 s23, s23, 0x100
	s_addc_u32 s25, s25, 0
	s_cmp_gt_u32 s45, 29
	s_barrier
	s_cbranch_scc0 .LBB0_413
	s_and_b64 vcc, exec, s[78:79]
	s_cbranch_vccz .LBB0_416
	s_barrier

.Lsprio_p5:
.LBB0_507:
	ds_read_b128 v[166:169], v163
	ds_read_b128 v[170:173], v163 offset:1024
	ds_read_b128 v[174:177], v163 offset:2048
	ds_read_b128 v[178:181], v163 offset:3072
	ds_read_b128 v[182:185], v164
	ds_read_b128 v[188:191], v164 offset:1024
	ds_read_b128 v[192:195], v164 offset:2048
	ds_read_b128 v[196:199], v164 offset:3072
	s_add_u32 s44, s42, 0xfff80080
	s_addc_u32 s45, s43, -1
	s_cmp_eq_u32 s52, 28
	s_cselect_b32 s47, s7, s45
	s_cselect_b32 s46, s6, s44
	s_cselect_b32 s45, s23, s21
	s_cselect_b32 s44, s22, s17
	s_add_u32 s54, s44, 0x80000
	s_addc_u32 s55, s45, 0
	s_mov_b32 m0, s94
	ds_read_b128 v[200:203], v165
	ds_read_b128 v[204:207], v165 offset:1024
	ds_read_b128 v[208:211], v165 offset:2048
	ds_read_b128 v[212:215], v165 offset:3072
	ds_read_b128 v[216:219], v165 offset:4096
	ds_read_b128 v[220:223], v165 offset:5120
	ds_read_b128 v[224:227], v165 offset:6144
	ds_read_b128 v[228:231], v165 offset:7168
	global_load_lds_dwordx4 v152, s[42:43]
	s_mov_b32 m0, s95
	s_nop 0
	global_load_lds_dwordx4 v154, s[42:43]
	s_waitcnt vmcnt(8)
	s_waitcnt lgkmcnt(0)
	s_barrier
	s_waitcnt lgkmcnt(0)
	v_mfma_f32_16x16x32_bf16 v[124:127], v[166:169], v[200:203], v[124:127]
	v_mfma_f32_16x16x32_bf16 v[120:123], v[174:177], v[200:203], v[120:123]
	v_mfma_f32_16x16x32_bf16 v[108:111], v[166:169], v[208:211], v[108:111]
	v_mfma_f32_16x16x32_bf16 v[104:107], v[174:177], v[208:211], v[104:107]
	v_mfma_f32_16x16x32_bf16 v[92:95], v[166:169], v[216:219], v[92:95]
	v_mfma_f32_16x16x32_bf16 v[88:91], v[174:177], v[216:219], v[88:91]
	v_mfma_f32_16x16x32_bf16 v[76:79], v[166:169], v[224:227], v[76:79]
	v_mfma_f32_16x16x32_bf16 v[72:75], v[174:177], v[224:227], v[72:75]
	v_mfma_f32_16x16x32_bf16 v[124:127], v[170:173], v[204:207], v[124:127]
	v_mfma_f32_16x16x32_bf16 v[120:123], v[178:181], v[204:207], v[120:123]
	v_mfma_f32_16x16x32_bf16 v[108:111], v[170:173], v[212:215], v[108:111]
	v_mfma_f32_16x16x32_bf16 v[104:107], v[178:181], v[212:215], v[104:107]
	v_mfma_f32_16x16x32_bf16 v[92:95], v[170:173], v[220:223], v[92:95]
	v_mfma_f32_16x16x32_bf16 v[88:91], v[178:181], v[220:223], v[88:91]
	v_mfma_f32_16x16x32_bf16 v[76:79], v[170:173], v[228:231], v[76:79]
	v_mfma_f32_16x16x32_bf16 v[72:75], v[178:181], v[228:231], v[72:75]
	v_mfma_f32_16x16x32_bf16 v[116:119], v[182:185], v[200:203], v[116:119]
	v_mfma_f32_16x16x32_bf16 v[112:115], v[192:195], v[200:203], v[112:115]
	v_mfma_f32_16x16x32_bf16 v[100:103], v[182:185], v[208:211], v[100:103]
	v_mfma_f32_16x16x32_bf16 v[96:99], v[192:195], v[208:211], v[96:99]
	v_mfma_f32_16x16x32_bf16 v[84:87], v[182:185], v[216:219], v[84:87]
	v_mfma_f32_16x16x32_bf16 v[80:83], v[192:195], v[216:219], v[80:83]
	v_mfma_f32_16x16x32_bf16 v[68:71], v[182:185], v[224:227], v[68:71]
	v_mfma_f32_16x16x32_bf16 v[64:67], v[192:195], v[224:227], v[64:67]
	v_mfma_f32_16x16x32_bf16 v[116:119], v[188:191], v[204:207], v[116:119]
	v_mfma_f32_16x16x32_bf16 v[112:115], v[196:199], v[204:207], v[112:115]
	v_mfma_f32_16x16x32_bf16 v[100:103], v[188:191], v[212:215], v[100:103]
	v_mfma_f32_16x16x32_bf16 v[96:99], v[196:199], v[212:215], v[96:99]
	v_mfma_f32_16x16x32_bf16 v[84:87], v[188:191], v[220:223], v[84:87]
	v_mfma_f32_16x16x32_bf16 v[80:83], v[196:199], v[220:223], v[80:83]
	v_mfma_f32_16x16x32_bf16 v[68:71], v[188:191], v[228:231], v[68:71]
	v_mfma_f32_16x16x32_bf16 v[64:67], v[196:199], v[228:231], v[64:67]
	s_barrier
	s_mov_b32 m0, s96
	s_add_u32 s98, s46, 0x80000
	s_addc_u32 s99, s47, 0
	ds_read_b128 v[200:203], v165 offset:16384
	ds_read_b128 v[204:207], v165 offset:17408
	ds_read_b128 v[208:211], v165 offset:18432
	ds_read_b128 v[212:215], v165 offset:19456
	ds_read_b128 v[216:219], v165 offset:20480
	ds_read_b128 v[220:223], v165 offset:21504
	ds_read_b128 v[224:227], v165 offset:22528
	ds_read_b128 v[228:231], v165 offset:23552
	global_load_lds_dwordx4 v130, s[44:45]
	s_mov_b32 m0, s97
	s_nop 0
	global_load_lds_dwordx4 v134, s[44:45]
	s_mov_b32 m0, s91
	s_nop 0
	global_load_lds_dwordx4 v130, s[54:55]
	s_mov_b32 m0, s26
	s_nop 0
	global_load_lds_dwordx4 v134, s[54:55]
	s_mov_b32 m0, s33
	s_nop 0
	global_load_lds_dwordx4 v128, s[46:47]
	s_mov_b32 m0, s88
	s_nop 0
	global_load_lds_dwordx4 v132, s[46:47]
	s_waitcnt vmcnt(8)
	s_waitcnt lgkmcnt(0)
	s_barrier
	s_waitcnt lgkmcnt(0)
	v_mfma_f32_16x16x32_bf16 v[60:63], v[166:169], v[200:203], v[60:63]
	v_mfma_f32_16x16x32_bf16 v[56:59], v[174:177], v[200:203], v[56:59]
	v_mfma_f32_16x16x32_bf16 v[44:47], v[166:169], v[208:211], v[44:47]
	v_mfma_f32_16x16x32_bf16 v[40:43], v[174:177], v[208:211], v[40:43]
	v_mfma_f32_16x16x32_bf16 v[28:31], v[166:169], v[216:219], v[28:31]
	v_mfma_f32_16x16x32_bf16 v[24:27], v[174:177], v[216:219], v[24:27]
	v_mfma_f32_16x16x32_bf16 v[12:15], v[166:169], v[224:227], v[12:15]
	v_mfma_f32_16x16x32_bf16 v[8:11], v[174:177], v[224:227], v[8:11]
	v_mfma_f32_16x16x32_bf16 v[60:63], v[170:173], v[204:207], v[60:63]
	v_mfma_f32_16x16x32_bf16 v[56:59], v[178:181], v[204:207], v[56:59]
	v_mfma_f32_16x16x32_bf16 v[44:47], v[170:173], v[212:215], v[44:47]
	v_mfma_f32_16x16x32_bf16 v[40:43], v[178:181], v[212:215], v[40:43]
	v_mfma_f32_16x16x32_bf16 v[28:31], v[170:173], v[220:223], v[28:31]
	v_mfma_f32_16x16x32_bf16 v[24:27], v[178:181], v[220:223], v[24:27]
	v_mfma_f32_16x16x32_bf16 v[12:15], v[170:173], v[228:231], v[12:15]
	v_mfma_f32_16x16x32_bf16 v[8:11], v[178:181], v[228:231], v[8:11]
	v_mfma_f32_16x16x32_bf16 v[52:55], v[182:185], v[200:203], v[52:55]
	v_mfma_f32_16x16x32_bf16 v[48:51], v[192:195], v[200:203], v[48:51]
	v_mfma_f32_16x16x32_bf16 v[36:39], v[182:185], v[208:211], v[36:39]
	v_mfma_f32_16x16x32_bf16 v[32:35], v[192:195], v[208:211], v[32:35]
	v_mfma_f32_16x16x32_bf16 v[20:23], v[182:185], v[216:219], v[20:23]
	v_mfma_f32_16x16x32_bf16 v[16:19], v[192:195], v[216:219], v[16:19]
	v_mfma_f32_16x16x32_bf16 v[4:7], v[182:185], v[224:227], v[4:7]
	v_mfma_f32_16x16x32_bf16 v[0:3], v[192:195], v[224:227], v[0:3]
	v_mfma_f32_16x16x32_bf16 v[52:55], v[188:191], v[204:207], v[52:55]
	v_mfma_f32_16x16x32_bf16 v[48:51], v[196:199], v[204:207], v[48:51]
	v_mfma_f32_16x16x32_bf16 v[36:39], v[188:191], v[212:215], v[36:39]
	v_mfma_f32_16x16x32_bf16 v[32:35], v[196:199], v[212:215], v[32:35]
	v_mfma_f32_16x16x32_bf16 v[20:23], v[188:191], v[220:223], v[20:23]
	v_mfma_f32_16x16x32_bf16 v[16:19], v[196:199], v[220:223], v[16:19]
	v_mfma_f32_16x16x32_bf16 v[4:7], v[188:191], v[228:231], v[4:7]
	v_mfma_f32_16x16x32_bf16 v[0:3], v[196:199], v[228:231], v[0:3]
	s_barrier
	v_add_u32_e32 v178, s29, v162
	v_add_u32_e32 v187, s41, v162
	ds_read_b128 v[166:169], v178
	ds_read_b128 v[170:173], v178 offset:1024
	ds_read_b128 v[174:177], v178 offset:2048
	ds_read_b128 v[178:181], v178 offset:3072
	ds_read_b128 v[182:185], v187
	ds_read_b128 v[188:191], v187 offset:1024
	ds_read_b128 v[192:195], v187 offset:2048
	ds_read_b128 v[196:199], v187 offset:3072
	s_mov_b32 m0, s89
	s_add_u32 s100, s44, 0x80
	s_addc_u32 s101, s45, 0
	ds_read_b128 v[200:203], v165 offset:32768
	ds_read_b128 v[204:207], v165 offset:33792
	ds_read_b128 v[208:211], v165 offset:34816
	ds_read_b128 v[212:215], v165 offset:35840
	ds_read_b128 v[216:219], v165 offset:36864
	ds_read_b128 v[220:223], v165 offset:37888
	ds_read_b128 v[224:227], v165 offset:38912
	ds_read_b128 v[228:231], v165 offset:39936
	global_load_lds_dwordx4 v128, s[98:99]
	s_mov_b32 m0, s90
	s_add_u32 s54, s44, 0x80080
	s_addc_u32 s55, s45, 0
	global_load_lds_dwordx4 v132, s[98:99]
	s_add_u32 s98, s46, 0x80
	s_addc_u32 s99, s47, 0
	s_waitcnt vmcnt(8)
	s_waitcnt lgkmcnt(0)
	s_barrier
	s_waitcnt lgkmcnt(0)
	v_mfma_f32_16x16x32_bf16 v[124:127], v[166:169], v[200:203], v[124:127]
	v_mfma_f32_16x16x32_bf16 v[120:123], v[174:177], v[200:203], v[120:123]
	v_mfma_f32_16x16x32_bf16 v[108:111], v[166:169], v[208:211], v[108:111]
	v_mfma_f32_16x16x32_bf16 v[104:107], v[174:177], v[208:211], v[104:107]
	v_mfma_f32_16x16x32_bf16 v[92:95], v[166:169], v[216:219], v[92:95]
	v_mfma_f32_16x16x32_bf16 v[88:91], v[174:177], v[216:219], v[88:91]
	v_mfma_f32_16x16x32_bf16 v[76:79], v[166:169], v[224:227], v[76:79]
	v_mfma_f32_16x16x32_bf16 v[72:75], v[174:177], v[224:227], v[72:75]
	v_mfma_f32_16x16x32_bf16 v[124:127], v[170:173], v[204:207], v[124:127]
	v_mfma_f32_16x16x32_bf16 v[120:123], v[178:181], v[204:207], v[120:123]
	v_mfma_f32_16x16x32_bf16 v[108:111], v[170:173], v[212:215], v[108:111]
	v_mfma_f32_16x16x32_bf16 v[104:107], v[178:181], v[212:215], v[104:107]
	v_mfma_f32_16x16x32_bf16 v[92:95], v[170:173], v[220:223], v[92:95]
	v_mfma_f32_16x16x32_bf16 v[88:91], v[178:181], v[220:223], v[88:91]
	v_mfma_f32_16x16x32_bf16 v[76:79], v[170:173], v[228:231], v[76:79]
	v_mfma_f32_16x16x32_bf16 v[72:75], v[178:181], v[228:231], v[72:75]
	v_mfma_f32_16x16x32_bf16 v[116:119], v[182:185], v[200:203], v[116:119]
	v_mfma_f32_16x16x32_bf16 v[112:115], v[192:195], v[200:203], v[112:115]
	v_mfma_f32_16x16x32_bf16 v[100:103], v[182:185], v[208:211], v[100:103]
	v_mfma_f32_16x16x32_bf16 v[96:99], v[192:195], v[208:211], v[96:99]
	v_mfma_f32_16x16x32_bf16 v[84:87], v[182:185], v[216:219], v[84:87]
	v_mfma_f32_16x16x32_bf16 v[80:83], v[192:195], v[216:219], v[80:83]
	v_mfma_f32_16x16x32_bf16 v[68:71], v[182:185], v[224:227], v[68:71]
	v_mfma_f32_16x16x32_bf16 v[64:67], v[192:195], v[224:227], v[64:67]
	v_mfma_f32_16x16x32_bf16 v[116:119], v[188:191], v[204:207], v[116:119]
	v_mfma_f32_16x16x32_bf16 v[112:115], v[196:199], v[204:207], v[112:115]
	v_mfma_f32_16x16x32_bf16 v[100:103], v[188:191], v[212:215], v[100:103]
	v_mfma_f32_16x16x32_bf16 v[96:99], v[196:199], v[212:215], v[96:99]
	v_mfma_f32_16x16x32_bf16 v[84:87], v[188:191], v[220:223], v[84:87]
	v_mfma_f32_16x16x32_bf16 v[80:83], v[196:199], v[220:223], v[80:83]
	v_mfma_f32_16x16x32_bf16 v[68:71], v[188:191], v[228:231], v[68:71]
	v_mfma_f32_16x16x32_bf16 v[64:67], v[196:199], v[228:231], v[64:67]
	s_barrier
	s_mov_b32 m0, s27
	s_nop 0
	ds_read_b128 v[200:203], v165 offset:49152
	ds_read_b128 v[204:207], v165 offset:50176
	ds_read_b128 v[208:211], v165 offset:51200
	ds_read_b128 v[212:215], v165 offset:52224
	ds_read_b128 v[216:219], v165 offset:53248
	ds_read_b128 v[220:223], v165 offset:54272
	ds_read_b128 v[224:227], v165 offset:55296
	ds_read_b128 v[228:231], v165 offset:56320
	global_load_lds_dwordx4 v130, s[100:101]
	s_mov_b32 m0, s34
	s_nop 0
	global_load_lds_dwordx4 v134, s[100:101]
	s_mov_b32 m0, s35
	s_nop 0
	global_load_lds_dwordx4 v130, s[54:55]
	s_mov_b32 m0, s28
	s_nop 0
	global_load_lds_dwordx4 v134, s[54:55]
	s_mov_b32 m0, s92
	s_nop 0
	global_load_lds_dwordx4 v128, s[98:99]
	s_mov_b32 m0, s93
	s_nop 0
	global_load_lds_dwordx4 v132, s[98:99]
	s_waitcnt vmcnt(8)
	s_waitcnt lgkmcnt(0)
	s_barrier
	s_waitcnt lgkmcnt(0)
	v_mfma_f32_16x16x32_bf16 v[60:63], v[166:169], v[200:203], v[60:63]
	v_mfma_f32_16x16x32_bf16 v[56:59], v[174:177], v[200:203], v[56:59]
	v_mfma_f32_16x16x32_bf16 v[44:47], v[166:169], v[208:211], v[44:47]
	v_mfma_f32_16x16x32_bf16 v[40:43], v[174:177], v[208:211], v[40:43]
	v_mfma_f32_16x16x32_bf16 v[28:31], v[166:169], v[216:219], v[28:31]
	v_mfma_f32_16x16x32_bf16 v[24:27], v[174:177], v[216:219], v[24:27]
	v_mfma_f32_16x16x32_bf16 v[12:15], v[166:169], v[224:227], v[12:15]
	v_mfma_f32_16x16x32_bf16 v[8:11], v[174:177], v[224:227], v[8:11]
	v_mfma_f32_16x16x32_bf16 v[60:63], v[170:173], v[204:207], v[60:63]
	v_mfma_f32_16x16x32_bf16 v[56:59], v[178:181], v[204:207], v[56:59]
	v_mfma_f32_16x16x32_bf16 v[44:47], v[170:173], v[212:215], v[44:47]
	v_mfma_f32_16x16x32_bf16 v[40:43], v[178:181], v[212:215], v[40:43]
	v_mfma_f32_16x16x32_bf16 v[28:31], v[170:173], v[220:223], v[28:31]
	v_mfma_f32_16x16x32_bf16 v[24:27], v[178:181], v[220:223], v[24:27]
	v_mfma_f32_16x16x32_bf16 v[12:15], v[170:173], v[228:231], v[12:15]
	v_mfma_f32_16x16x32_bf16 v[8:11], v[178:181], v[228:231], v[8:11]
	v_mfma_f32_16x16x32_bf16 v[52:55], v[182:185], v[200:203], v[52:55]
	v_mfma_f32_16x16x32_bf16 v[48:51], v[192:195], v[200:203], v[48:51]
	v_mfma_f32_16x16x32_bf16 v[36:39], v[182:185], v[208:211], v[36:39]
	v_mfma_f32_16x16x32_bf16 v[32:35], v[192:195], v[208:211], v[32:35]
	v_mfma_f32_16x16x32_bf16 v[20:23], v[182:185], v[216:219], v[20:23]
	v_mfma_f32_16x16x32_bf16 v[16:19], v[192:195], v[216:219], v[16:19]
	v_mfma_f32_16x16x32_bf16 v[4:7], v[182:185], v[224:227], v[4:7]
	v_mfma_f32_16x16x32_bf16 v[0:3], v[192:195], v[224:227], v[0:3]
	v_mfma_f32_16x16x32_bf16 v[52:55], v[188:191], v[204:207], v[52:55]
	v_mfma_f32_16x16x32_bf16 v[48:51], v[196:199], v[204:207], v[48:51]
	v_mfma_f32_16x16x32_bf16 v[36:39], v[188:191], v[212:215], v[36:39]
	v_mfma_f32_16x16x32_bf16 v[32:35], v[196:199], v[212:215], v[32:35]
	v_mfma_f32_16x16x32_bf16 v[20:23], v[188:191], v[220:223], v[20:23]
	v_mfma_f32_16x16x32_bf16 v[16:19], v[196:199], v[220:223], v[16:19]
	v_mfma_f32_16x16x32_bf16 v[4:7], v[188:191], v[228:231], v[4:7]
	v_mfma_f32_16x16x32_bf16 v[0:3], v[196:199], v[228:231], v[0:3]
	s_add_i32 s52, s52, 2
	s_add_u32 s42, s42, 0x100
	s_addc_u32 s43, s43, 0
	s_add_u32 s17, s17, 0x100
	s_addc_u32 s21, s21, 0
	s_cmp_gt_u32 s52, 29
	s_barrier
	s_cbranch_scc0 .LBB0_507
	s_setprio 0
	s_and_b64 vcc, exec, s[78:79]
	s_cbranch_vccz .LBB0_510
	s_barrier

.Lsprio_p6:
.LBB0_674:
	ds_read_b128 v[128:131], v174
	ds_read_b128 v[132:135], v174 offset:1024
	ds_read_b128 v[148:151], v174 offset:2048
	ds_read_b128 v[152:155], v174 offset:3072
	ds_read_b128 v[156:159], v175
	ds_read_b128 v[160:163], v175 offset:1024
	ds_read_b128 v[164:167], v175 offset:2048
	ds_read_b128 v[168:171], v175 offset:3072
	s_add_u32 s36, s24, 0x4000
	s_addc_u32 s37, s25, 0
	s_cmpk_eq_i32 s45, 0x7c
	s_cselect_b32 s40, s29, s36
	s_cselect_b32 s41, s3, s37
	s_cselect_b32 s38, s4, s30
	s_cselect_b32 s39, s5, s31
	s_add_u32 s36, s40, 0x8000
	s_addc_u32 s37, s41, 0
	s_add_u32 s46, s38, 0x200000
	s_addc_u32 s47, s39, 0
	s_mov_b32 m0, s94
	ds_read_b128 v[182:185], v176
	ds_read_b128 v[188:191], v176 offset:1024
	ds_read_b128 v[192:195], v176 offset:2048
	ds_read_b128 v[196:199], v176 offset:3072
	ds_read_b128 v[200:203], v176 offset:4096
	ds_read_b128 v[204:207], v176 offset:5120
	ds_read_b128 v[208:211], v176 offset:6144
	ds_read_b128 v[212:215], v176 offset:7168
	global_load_lds_dwordx4 v144, s[24:25]
	s_mov_b32 m0, s95
	s_nop 0
	global_load_lds_dwordx4 v146, s[24:25]
	s_waitcnt vmcnt(8)
	s_waitcnt lgkmcnt(0)
	s_barrier
	s_waitcnt lgkmcnt(0)
	v_mfma_f32_16x16x32_bf16 v[124:127], v[128:131], v[182:185], v[124:127]
	v_mfma_f32_16x16x32_bf16 v[120:123], v[148:151], v[182:185], v[120:123]
	v_mfma_f32_16x16x32_bf16 v[108:111], v[128:131], v[192:195], v[108:111]
	v_mfma_f32_16x16x32_bf16 v[104:107], v[148:151], v[192:195], v[104:107]
	v_mfma_f32_16x16x32_bf16 v[92:95], v[128:131], v[200:203], v[92:95]
	v_mfma_f32_16x16x32_bf16 v[88:91], v[148:151], v[200:203], v[88:91]
	v_mfma_f32_16x16x32_bf16 v[76:79], v[128:131], v[208:211], v[76:79]
	v_mfma_f32_16x16x32_bf16 v[72:75], v[148:151], v[208:211], v[72:75]
	v_mfma_f32_16x16x32_bf16 v[124:127], v[132:135], v[188:191], v[124:127]
	v_mfma_f32_16x16x32_bf16 v[120:123], v[152:155], v[188:191], v[120:123]
	v_mfma_f32_16x16x32_bf16 v[108:111], v[132:135], v[196:199], v[108:111]
	v_mfma_f32_16x16x32_bf16 v[104:107], v[152:155], v[196:199], v[104:107]
	v_mfma_f32_16x16x32_bf16 v[92:95], v[132:135], v[204:207], v[92:95]
	v_mfma_f32_16x16x32_bf16 v[88:91], v[152:155], v[204:207], v[88:91]
	v_mfma_f32_16x16x32_bf16 v[76:79], v[132:135], v[212:215], v[76:79]
	v_mfma_f32_16x16x32_bf16 v[72:75], v[152:155], v[212:215], v[72:75]
	v_mfma_f32_16x16x32_bf16 v[116:119], v[156:159], v[182:185], v[116:119]
	v_mfma_f32_16x16x32_bf16 v[112:115], v[164:167], v[182:185], v[112:115]
	v_mfma_f32_16x16x32_bf16 v[100:103], v[156:159], v[192:195], v[100:103]
	v_mfma_f32_16x16x32_bf16 v[96:99], v[164:167], v[192:195], v[96:99]
	v_mfma_f32_16x16x32_bf16 v[84:87], v[156:159], v[200:203], v[84:87]
	v_mfma_f32_16x16x32_bf16 v[80:83], v[164:167], v[200:203], v[80:83]
	v_mfma_f32_16x16x32_bf16 v[68:71], v[156:159], v[208:211], v[68:71]
	v_mfma_f32_16x16x32_bf16 v[64:67], v[164:167], v[208:211], v[64:67]
	v_mfma_f32_16x16x32_bf16 v[116:119], v[160:163], v[188:191], v[116:119]
	v_mfma_f32_16x16x32_bf16 v[112:115], v[168:171], v[188:191], v[112:115]
	v_mfma_f32_16x16x32_bf16 v[100:103], v[160:163], v[196:199], v[100:103]
	v_mfma_f32_16x16x32_bf16 v[96:99], v[168:171], v[196:199], v[96:99]
	v_mfma_f32_16x16x32_bf16 v[84:87], v[160:163], v[204:207], v[84:87]
	v_mfma_f32_16x16x32_bf16 v[80:83], v[168:171], v[204:207], v[80:83]
	v_mfma_f32_16x16x32_bf16 v[68:71], v[160:163], v[212:215], v[68:71]
	v_mfma_f32_16x16x32_bf16 v[64:67], v[168:171], v[212:215], v[64:67]
	s_barrier
	s_mov_b32 m0, s96
	s_add_u32 s98, s40, 0x4000
	s_addc_u32 s99, s41, 0
	ds_read_b128 v[182:185], v176 offset:16384
	ds_read_b128 v[188:191], v176 offset:17408
	ds_read_b128 v[192:195], v176 offset:18432
	ds_read_b128 v[196:199], v176 offset:19456
	ds_read_b128 v[200:203], v176 offset:20480
	ds_read_b128 v[204:207], v176 offset:21504
	ds_read_b128 v[208:211], v176 offset:22528
	ds_read_b128 v[212:215], v176 offset:23552
	global_load_lds_dwordx4 v138, s[38:39]
	s_mov_b32 m0, s97
	s_nop 0
	global_load_lds_dwordx4 v142, s[38:39]
	s_mov_b32 m0, s91
	s_nop 0
	global_load_lds_dwordx4 v138, s[46:47]
	s_mov_b32 m0, s26
	s_nop 0
	global_load_lds_dwordx4 v142, s[46:47]
	s_mov_b32 m0, s33
	s_nop 0
	global_load_lds_dwordx4 v136, s[40:41]
	s_mov_b32 m0, s88
	s_nop 0
	global_load_lds_dwordx4 v140, s[40:41]
	s_waitcnt vmcnt(8)
	s_waitcnt lgkmcnt(0)
	s_barrier
	s_waitcnt lgkmcnt(0)
	v_mfma_f32_16x16x32_bf16 v[60:63], v[128:131], v[182:185], v[60:63]
	v_mfma_f32_16x16x32_bf16 v[56:59], v[148:151], v[182:185], v[56:59]
	v_mfma_f32_16x16x32_bf16 v[44:47], v[128:131], v[192:195], v[44:47]
	v_mfma_f32_16x16x32_bf16 v[40:43], v[148:151], v[192:195], v[40:43]
	v_mfma_f32_16x16x32_bf16 v[28:31], v[128:131], v[200:203], v[28:31]
	v_mfma_f32_16x16x32_bf16 v[24:27], v[148:151], v[200:203], v[24:27]
	v_mfma_f32_16x16x32_bf16 v[12:15], v[128:131], v[208:211], v[12:15]
	v_mfma_f32_16x16x32_bf16 v[8:11], v[148:151], v[208:211], v[8:11]
	v_mfma_f32_16x16x32_bf16 v[60:63], v[132:135], v[188:191], v[60:63]
	v_mfma_f32_16x16x32_bf16 v[56:59], v[152:155], v[188:191], v[56:59]
	v_mfma_f32_16x16x32_bf16 v[44:47], v[132:135], v[196:199], v[44:47]
	v_mfma_f32_16x16x32_bf16 v[40:43], v[152:155], v[196:199], v[40:43]
	v_mfma_f32_16x16x32_bf16 v[28:31], v[132:135], v[204:207], v[28:31]
	v_mfma_f32_16x16x32_bf16 v[24:27], v[152:155], v[204:207], v[24:27]
	v_mfma_f32_16x16x32_bf16 v[12:15], v[132:135], v[212:215], v[12:15]
	v_mfma_f32_16x16x32_bf16 v[8:11], v[152:155], v[212:215], v[8:11]
	v_mfma_f32_16x16x32_bf16 v[52:55], v[156:159], v[182:185], v[52:55]
	v_mfma_f32_16x16x32_bf16 v[48:51], v[164:167], v[182:185], v[48:51]
	v_mfma_f32_16x16x32_bf16 v[36:39], v[156:159], v[192:195], v[36:39]
	v_mfma_f32_16x16x32_bf16 v[32:35], v[164:167], v[192:195], v[32:35]
	v_mfma_f32_16x16x32_bf16 v[20:23], v[156:159], v[200:203], v[20:23]
	v_mfma_f32_16x16x32_bf16 v[16:19], v[164:167], v[200:203], v[16:19]
	v_mfma_f32_16x16x32_bf16 v[4:7], v[156:159], v[208:211], v[4:7]
	v_mfma_f32_16x16x32_bf16 v[0:3], v[164:167], v[208:211], v[0:3]
	v_mfma_f32_16x16x32_bf16 v[52:55], v[160:163], v[188:191], v[52:55]
	v_mfma_f32_16x16x32_bf16 v[48:51], v[168:171], v[188:191], v[48:51]
	v_mfma_f32_16x16x32_bf16 v[36:39], v[160:163], v[196:199], v[36:39]
	v_mfma_f32_16x16x32_bf16 v[32:35], v[168:171], v[196:199], v[32:35]
	v_mfma_f32_16x16x32_bf16 v[20:23], v[160:163], v[204:207], v[20:23]
	v_mfma_f32_16x16x32_bf16 v[16:19], v[168:171], v[204:207], v[16:19]
	v_mfma_f32_16x16x32_bf16 v[4:7], v[160:163], v[212:215], v[4:7]
	v_mfma_f32_16x16x32_bf16 v[0:3], v[168:171], v[212:215], v[0:3]
	s_barrier
	ds_read_b128 v[128:131], v179
	ds_read_b128 v[132:135], v179 offset:1024
	ds_read_b128 v[148:151], v179 offset:2048
	ds_read_b128 v[152:155], v179 offset:3072
	ds_read_b128 v[156:159], v180
	ds_read_b128 v[160:163], v180 offset:1024
	ds_read_b128 v[164:167], v180 offset:2048
	ds_read_b128 v[168:171], v180 offset:3072
	s_mov_b32 m0, s89
	s_add_u32 s100, s38, 0x80
	s_addc_u32 s101, s39, 0
	ds_read_b128 v[182:185], v176 offset:32768
	ds_read_b128 v[188:191], v176 offset:33792
	ds_read_b128 v[192:195], v176 offset:34816
	ds_read_b128 v[196:199], v176 offset:35840
	ds_read_b128 v[200:203], v176 offset:36864
	ds_read_b128 v[204:207], v176 offset:37888
	ds_read_b128 v[208:211], v176 offset:38912
	ds_read_b128 v[212:215], v176 offset:39936
	global_load_lds_dwordx4 v136, s[98:99]
	s_mov_b32 m0, s90
	s_add_u32 s46, s38, 0x200080
	s_addc_u32 s47, s39, 0
	global_load_lds_dwordx4 v140, s[98:99]
	s_waitcnt vmcnt(8)
	s_waitcnt lgkmcnt(0)
	s_barrier
	s_waitcnt lgkmcnt(0)
	v_mfma_f32_16x16x32_bf16 v[124:127], v[128:131], v[182:185], v[124:127]
	v_mfma_f32_16x16x32_bf16 v[120:123], v[148:151], v[182:185], v[120:123]
	v_mfma_f32_16x16x32_bf16 v[108:111], v[128:131], v[192:195], v[108:111]
	v_mfma_f32_16x16x32_bf16 v[104:107], v[148:151], v[192:195], v[104:107]
	v_mfma_f32_16x16x32_bf16 v[92:95], v[128:131], v[200:203], v[92:95]
	v_mfma_f32_16x16x32_bf16 v[88:91], v[148:151], v[200:203], v[88:91]
	v_mfma_f32_16x16x32_bf16 v[76:79], v[128:131], v[208:211], v[76:79]
	v_mfma_f32_16x16x32_bf16 v[72:75], v[148:151], v[208:211], v[72:75]
	v_mfma_f32_16x16x32_bf16 v[124:127], v[132:135], v[188:191], v[124:127]
	v_mfma_f32_16x16x32_bf16 v[120:123], v[152:155], v[188:191], v[120:123]
	v_mfma_f32_16x16x32_bf16 v[108:111], v[132:135], v[196:199], v[108:111]
	v_mfma_f32_16x16x32_bf16 v[104:107], v[152:155], v[196:199], v[104:107]
	v_mfma_f32_16x16x32_bf16 v[92:95], v[132:135], v[204:207], v[92:95]
	v_mfma_f32_16x16x32_bf16 v[88:91], v[152:155], v[204:207], v[88:91]
	v_mfma_f32_16x16x32_bf16 v[76:79], v[132:135], v[212:215], v[76:79]
	v_mfma_f32_16x16x32_bf16 v[72:75], v[152:155], v[212:215], v[72:75]
	v_mfma_f32_16x16x32_bf16 v[116:119], v[156:159], v[182:185], v[116:119]
	v_mfma_f32_16x16x32_bf16 v[112:115], v[164:167], v[182:185], v[112:115]
	v_mfma_f32_16x16x32_bf16 v[100:103], v[156:159], v[192:195], v[100:103]
	v_mfma_f32_16x16x32_bf16 v[96:99], v[164:167], v[192:195], v[96:99]
	v_mfma_f32_16x16x32_bf16 v[84:87], v[156:159], v[200:203], v[84:87]
	v_mfma_f32_16x16x32_bf16 v[80:83], v[164:167], v[200:203], v[80:83]
	v_mfma_f32_16x16x32_bf16 v[68:71], v[156:159], v[208:211], v[68:71]
	v_mfma_f32_16x16x32_bf16 v[64:67], v[164:167], v[208:211], v[64:67]
	v_mfma_f32_16x16x32_bf16 v[116:119], v[160:163], v[188:191], v[116:119]
	v_mfma_f32_16x16x32_bf16 v[112:115], v[168:171], v[188:191], v[112:115]
	v_mfma_f32_16x16x32_bf16 v[100:103], v[160:163], v[196:199], v[100:103]
	v_mfma_f32_16x16x32_bf16 v[96:99], v[168:171], v[196:199], v[96:99]
	v_mfma_f32_16x16x32_bf16 v[84:87], v[160:163], v[204:207], v[84:87]
	v_mfma_f32_16x16x32_bf16 v[80:83], v[168:171], v[204:207], v[80:83]
	v_mfma_f32_16x16x32_bf16 v[68:71], v[160:163], v[212:215], v[68:71]
	v_mfma_f32_16x16x32_bf16 v[64:67], v[168:171], v[212:215], v[64:67]
	s_barrier
	s_mov_b32 m0, s27
	s_nop 0
	ds_read_b128 v[182:185], v176 offset:49152
	ds_read_b128 v[188:191], v176 offset:50176
	ds_read_b128 v[192:195], v176 offset:51200
	ds_read_b128 v[196:199], v176 offset:52224
	ds_read_b128 v[200:203], v176 offset:53248
	ds_read_b128 v[204:207], v176 offset:54272
	ds_read_b128 v[208:211], v176 offset:55296
	ds_read_b128 v[212:215], v176 offset:56320
	global_load_lds_dwordx4 v138, s[100:101]
	s_mov_b32 m0, s34
	s_nop 0
	global_load_lds_dwordx4 v142, s[100:101]
	s_mov_b32 m0, s35
	s_nop 0
	global_load_lds_dwordx4 v138, s[46:47]
	s_mov_b32 m0, s28
	s_nop 0
	global_load_lds_dwordx4 v142, s[46:47]
	s_mov_b32 m0, s92
	s_nop 0
	global_load_lds_dwordx4 v136, s[36:37]
	s_mov_b32 m0, s93
	s_nop 0
	global_load_lds_dwordx4 v140, s[36:37]
	s_waitcnt vmcnt(8)
	s_waitcnt lgkmcnt(0)
	s_barrier
	s_waitcnt lgkmcnt(0)
	v_mfma_f32_16x16x32_bf16 v[60:63], v[128:131], v[182:185], v[60:63]
	v_mfma_f32_16x16x32_bf16 v[56:59], v[148:151], v[182:185], v[56:59]
	v_mfma_f32_16x16x32_bf16 v[44:47], v[128:131], v[192:195], v[44:47]
	v_mfma_f32_16x16x32_bf16 v[40:43], v[148:151], v[192:195], v[40:43]
	v_mfma_f32_16x16x32_bf16 v[28:31], v[128:131], v[200:203], v[28:31]
	v_mfma_f32_16x16x32_bf16 v[24:27], v[148:151], v[200:203], v[24:27]
	v_mfma_f32_16x16x32_bf16 v[12:15], v[128:131], v[208:211], v[12:15]
	v_mfma_f32_16x16x32_bf16 v[8:11], v[148:151], v[208:211], v[8:11]
	v_mfma_f32_16x16x32_bf16 v[60:63], v[132:135], v[188:191], v[60:63]
	v_mfma_f32_16x16x32_bf16 v[56:59], v[152:155], v[188:191], v[56:59]
	v_mfma_f32_16x16x32_bf16 v[44:47], v[132:135], v[196:199], v[44:47]
	v_mfma_f32_16x16x32_bf16 v[40:43], v[152:155], v[196:199], v[40:43]
	v_mfma_f32_16x16x32_bf16 v[28:31], v[132:135], v[204:207], v[28:31]
	v_mfma_f32_16x16x32_bf16 v[24:27], v[152:155], v[204:207], v[24:27]
	v_mfma_f32_16x16x32_bf16 v[12:15], v[132:135], v[212:215], v[12:15]
	v_mfma_f32_16x16x32_bf16 v[8:11], v[152:155], v[212:215], v[8:11]
	v_mfma_f32_16x16x32_bf16 v[52:55], v[156:159], v[182:185], v[52:55]
	v_mfma_f32_16x16x32_bf16 v[48:51], v[164:167], v[182:185], v[48:51]
	v_mfma_f32_16x16x32_bf16 v[36:39], v[156:159], v[192:195], v[36:39]
	v_mfma_f32_16x16x32_bf16 v[32:35], v[164:167], v[192:195], v[32:35]
	v_mfma_f32_16x16x32_bf16 v[20:23], v[156:159], v[200:203], v[20:23]
	v_mfma_f32_16x16x32_bf16 v[16:19], v[164:167], v[200:203], v[16:19]
	v_mfma_f32_16x16x32_bf16 v[4:7], v[156:159], v[208:211], v[4:7]
	v_mfma_f32_16x16x32_bf16 v[0:3], v[164:167], v[208:211], v[0:3]
	v_mfma_f32_16x16x32_bf16 v[52:55], v[160:163], v[188:191], v[52:55]
	v_mfma_f32_16x16x32_bf16 v[48:51], v[168:171], v[188:191], v[48:51]
	v_mfma_f32_16x16x32_bf16 v[36:39], v[160:163], v[196:199], v[36:39]
	v_mfma_f32_16x16x32_bf16 v[32:35], v[168:171], v[196:199], v[32:35]
	v_mfma_f32_16x16x32_bf16 v[20:23], v[160:163], v[204:207], v[20:23]
	v_mfma_f32_16x16x32_bf16 v[16:19], v[168:171], v[204:207], v[16:19]
	v_mfma_f32_16x16x32_bf16 v[4:7], v[160:163], v[212:215], v[4:7]
	v_mfma_f32_16x16x32_bf16 v[0:3], v[168:171], v[212:215], v[0:3]
	s_add_i32 s45, s45, 2
	s_add_u32 s30, s30, 0x100
	s_addc_u32 s31, s31, 0
	s_add_u32 s24, s24, 0x10000
	s_addc_u32 s25, s25, 0
	s_cmpk_gt_u32 s45, 0x7d
	s_barrier
	s_cbranch_scc0 .LBB0_674
	s_setprio 0
	s_and_b64 vcc, exec, s[78:79]
	s_cbranch_vccz .LBB0_677
	s_barrier
